# C-attention sink-load wait deferred past prologue barrier; redundant vmcnt(0) after A-near prologue barrier removed
# speedup vs baseline: 1.0347x; 1.0079x over previous
; template <int MODE, int NQ, int TS, bool FAST = false> ...
;     ...
;   for (int nq = 0; nq < NQ; ++nq) { const bf16_t* qp = proj + (size_t)(seq_base + TS * (q0w + 32 * nq + r32)) * ld + qoff + hh * 8;
; #pragma unroll
;     for (int ks = 0; ks < 4; ++ks) qf[nq][ks] = *(const bf16x8*)(qp + ks * 16); }
;   f32x16 o[NQ][2];
;   float m2[NQ], l[NQ];
; #pragma unroll
;   for (int nq = 0; nq < NQ; ++nq) {
;     if (MODE == 0) {
;       const size_t tok = (size_t)(seq_base + q0w + 32 * nq + r32);
;       const bf16_t* po = part_o + tok * 512 + ooff + 4 * hh; const float* pm = part_ml + (tok * 8 + (ooff >> 6)) * 2;
;       m2[nq] = pm[0]; l[nq] = hh ? 0.f : pm[1];
; #pragma unroll
;       for (int g = 0; g < 4; ++g) { const uint2 a = *(const uint2*)(po + 8 * g), b = *(const uint2*)(po + 32 + 8 * g);
;         o[nq][0][4 * g] = bflo(a.x); o[nq][0][4 * g + 1] = bfhi(a.x); o[nq][0][4 * g + 2] = bflo(a.y); o[nq][0][4 * g + 3] = bfhi(a.y);
;         o[nq][1][4 * g] = bflo(b.x); o[nq][1][4 * g + 1] = bfhi(b.x); o[nq][1][4 * g + 2] = bflo(b.y); o[nq][1][4 * g + 3] = bfhi(b.y); }
;     } else {
;       m2[nq] = (MODE == 2) ? sink2 : -1e30f; l[nq] = 0.f;
; #pragma unroll
;       for (int r = 0; r < 16; ++r) { o[nq][0][r] = 0.f; o[nq][1][r] = 0.f; }
;     }
;   }
;   PG8_LAS unsigned char* L = (PG8_LAS unsigned char*)lds;
;   const int kkey_ = wave * 8 + (lane >> 3);
;   const bf16_t* kg = proj + (size_t)(seq_base + TS * kkey_) * ld + koff + (((lane & 7) ^ ((kkey_ >> 1) & 7)) * 8);
;   const bf16_t* vg = proj + (size_t)(seq_base + TS * ((wave & 3) * 16 + (lane >> 2))) * ld + voff + ((wave >> 2) * 4 + (lane & 3)) * 8;
; DI void attn_phase_l1(const Params& p, char* lds) {
;     ...
;     const int kvh = u >> 8, tok0 = (u & 255) * 128;
;     const int seq_base = (tok0 < PROMPT_T) ? 0 : (PROMPT_T + ((tok0 - PROMPT_T) / SAMPLE_T) * SAMPLE_T);
;     const int T = (tok0 < PROMPT_T) ? PROMPT_T : SAMPLE_T;
;     const int q0 = tok0 - seq_base, head = kvh * 4 + (wave & 3);
;     int kt0 = (q0 - 128) >> 6; if (kt0 < 0) kt0 = 0;
;     int kt1 = ((q0 + 127 + 128) >> 6) + 1; if (kt1 > (T >> 6)) kt1 = T >> 6;
;     attn_unit<2, 2, 1>(p.big, 1536, seq_base, kt0, kt1, 1024 + kvh * 64, 1280 + kvh * 64, q0 + (wave >> 2) * 64, head * 64, head * 64,
;                        exp2f(-0.5f * (float)(head + 1)) * LOG2E, p.c_sink[head] * LOG2E, p.xn, lds, nullptr, nullptr);
.LBB0_224:
	s_ashr_i32 s0, s5, 8
	s_lshl_b32 s1, s5, 7
	s_and_b32 s8, s1, 0x7f80
	s_and_b32 s1, s1, 0x7000
	v_lshl_or_b32 v2, s0, 2, v163
	s_cmpk_lt_u32 s8, 0x4000
	v_add_u32_e32 v3, 1, v2
	s_cselect_b32 s7, 0, s1
	v_cvt_f32_i32_e32 v3, v3
	s_cselect_b32 s9, 0x100, 64
	s_sub_i32 s1, s8, s7
	s_add_i32 s8, s1, 0xffffff80
	s_ashr_i32 s8, s8, 6
	s_max_i32 s14, s8, 0
	s_add_i32 s8, s1, 0xff
	v_add_u32_e32 v0, s1, v165
	v_mul_f32_e32 v4, -0.5, v3
	s_mov_b32 s1, 0xc2fc0000
	v_cmp_gt_f32_e32 vcc, s1, v4
	v_readlane_b32 s80, v253, 16
	v_readlane_b32 s88, v253, 24
	v_cndmask_b32_e32 v4, 0, v233, vcc
	v_fmac_f32_e32 v4, -0.5, v3
	v_exp_f32_e32 v3, v4
	v_not_b32_e32 v4, 63
	v_cndmask_b32_e32 v4, 0, v4, vcc
	v_readlane_b32 s89, v253, 25
	v_ldexp_f32 v10, v3, v4
	v_ashrrev_i32_e32 v3, 31, v2
	v_lshlrev_b32_e32 v168, 6, v2
	v_lshl_add_u64 v[2:3], v[2:3], 2, s[88:89]
	global_load_dword v250, v[2:3], off
	v_mov_b32_e32 v3, v222
	s_ashr_i32 s8, s8, 6
	s_add_i32 s12, s8, 1
	v_bfe_u32 v184, v3, 5, 1
	v_ashrrev_i32_e32 v169, 31, v168
	s_cmp_lt_i32 s8, s9
	v_lshl_add_u64 v[6:7], v[168:169], 1, s[66:67]
	s_cselect_b32 s15, s12, s9
	s_movk_i32 s12, 0xc00
	v_and_b32_e32 v13, 3, v3
	s_mov_b32 s1, 0x1ffffffc
	v_mul_f32_e32 v10, 0xbfb8aa3b, v10
	s_lshl_b32 s0, s0, 6
	v_mov_b64_e32 v[4:5], s[66:67]
	s_mov_b64 s[18:19], 0x800
	s_add_i32 s26, s15, -1
	s_mov_b64 s[22:23], 0xa00
	s_mov_b32 s6, 0
	v_readlane_b32 s81, v253, 17
	v_readlane_b32 s82, v253, 18
	v_readlane_b32 s83, v253, 19
	v_readlane_b32 s84, v253, 20
	v_readlane_b32 s85, v253, 21
	v_readlane_b32 s86, v253, 22
	v_readlane_b32 s87, v253, 23
	v_readlane_b32 s90, v253, 26
	v_readlane_b32 s91, v253, 27
	v_readlane_b32 s92, v253, 28
	v_readlane_b32 s93, v253, 29
	v_readlane_b32 s94, v253, 30
	v_readlane_b32 s95, v253, 31
	v_and_b32_e32 v2, 31, v3
	v_or_b32_e32 v0, v0, v2
	v_add_u32_e32 v170, s7, v0
	v_lshlrev_b32_e32 v0, 4, v184
	v_lshl_add_u64 v[6:7], v[6:7], 0, v[0:1]
	v_mad_i64_i32 v[8:9], s[8:9], v170, s12, v[6:7]
	global_load_dwordx4 v[130:133], v[8:9], off
	global_load_dwordx4 v[134:137], v[8:9], off offset:32
	global_load_dwordx4 v[138:141], v[8:9], off offset:64
	global_load_dwordx4 v[142:145], v[8:9], off offset:96
	v_or_b32_e32 v166, 32, v170
	v_ashrrev_i32_e32 v8, 6, v3
	v_mad_i64_i32 v[6:7], s[8:9], v166, s12, v[6:7]
	v_and_b32_e32 v11, 3, v8
	global_load_dwordx4 v[146:149], v[6:7], off
	global_load_dwordx4 v[150:153], v[6:7], off offset:32
	global_load_dwordx4 v[154:157], v[6:7], off offset:64
	global_load_dwordx4 v[158:161], v[6:7], off offset:96
	v_lshlrev_b32_e32 v6, 4, v11
	v_bfe_u32 v7, v3, 2, 4
	v_or3_b32 v6, v6, v7, s7
	v_mul_u32_u24_e32 v12, 0x600, v6
	v_and_or_b32 v6, v8, s1, v13
	v_readfirstlane_b32 s1, v8
	s_lshl_b32 s16, s1, 10
	v_lshlrev_b32_e32 v14, 4, v8
	s_movk_i32 s1, 0xffc0
	v_bfi_b32 v14, s1, v14, v3
	s_movk_i32 s1, 0x100
	v_add_u32_e32 v15, 0xffffff00, v14
	v_cmp_gt_i32_e32 vcc, s1, v14
	v_sub_u32_e32 v16, 0x100, v14
	s_movk_i32 s8, 0x81
	v_cndmask_b32_e32 v15, v15, v16, vcc
	v_cmp_gt_i32_e32 vcc, s8, v15
	v_cvt_f32_i32_e32 v15, v15
	v_lshlrev_b32_e32 v11, 11, v11
	v_lshlrev_b32_e32 v16, 2, v14
	s_mov_b32 s1, 0x18000
	v_mul_f32_e32 v15, v10, v15
	v_add3_u32 v11, v16, v11, s1
	s_movk_i32 s1, 0x80
	v_cndmask_b32_e32 v15, v231, v15, vcc
	v_add_u32_e32 v16, 0xffffff80, v14
	v_cmp_gt_i32_e32 vcc, s1, v14
	v_sub_u32_e32 v17, 0x80, v14
	v_bfe_u32 v0, v3, 3, 3
	v_cndmask_b32_e32 v16, v16, v17, vcc
	v_cmp_gt_i32_e32 vcc, s8, v16
	v_cvt_f32_i32_e32 v16, v16
	v_lshl_or_b32 v0, v8, 3, v0
	s_movk_i32 s1, 0xff80
	v_add_u32_e32 v9, s7, v0
	v_mul_f32_e32 v16, v10, v16
	v_cndmask_b32_e32 v16, v231, v16, vcc
	ds_write2st64_b32 v11, v15, v16 offset1:2
	v_cmp_gt_i32_e32 vcc, 0, v8
	v_sub_u32_e32 v15, 0, v14
	v_lshrrev_b32_e32 v0, 1, v0
	v_cndmask_b32_e32 v15, v14, v15, vcc
	v_cmp_gt_i32_e32 vcc, s8, v15
	v_cvt_f32_i32_e32 v15, v15
	v_add_u32_e32 v16, 0x80, v14
	v_xor_b32_e32 v0, v0, v3
	v_lshlrev_b32_e32 v0, 4, v0
	v_mul_f32_e32 v15, v10, v15
	v_cndmask_b32_e32 v15, v231, v15, vcc
	v_cmp_gt_i32_e32 vcc, s1, v14
	v_sub_u32_e32 v14, 0xffffff80, v14
	s_ashr_i32 s1, s0, 31
	v_cndmask_b32_e32 v14, v16, v14, vcc
	v_cmp_gt_i32_e32 vcc, s8, v14
	v_mad_i64_i32 v[4:5], s[8:9], v9, s12, v[4:5]
	s_lshl_b64 s[0:1], s[0:1], 1
	v_cvt_f32_i32_e32 v14, v14
	v_lshl_add_u64 v[4:5], v[4:5], 0, s[0:1]
	v_and_b32_e32 v0, 0x70, v0
	v_lshl_add_u64 v[172:173], v[4:5], 0, v[0:1]
	v_lshlrev_b32_e32 v0, 1, v12
	v_lshlrev_b32_e32 v6, 3, v6
	v_lshl_add_u64 v[4:5], s[66:67], 0, v[0:1]
	v_ashrrev_i32_e32 v7, 31, v6
	v_lshl_add_u64 v[4:5], v[4:5], 0, s[0:1]
	v_mul_f32_e32 v10, v10, v14
	v_lshl_add_u64 v[174:175], v[6:7], 1, v[4:5]
	v_mad_u64_u32 v[4:5], s[0:1], s14, v232, v[172:173]
	v_cndmask_b32_e32 v10, v231, v10, vcc
	v_lshl_add_u64 v[4:5], v[4:5], 0, s[18:19]
	s_mov_b32 m0, s16
	ds_write2st64_b32 v11, v15, v10 offset0:4 offset1:6
	global_load_lds_dwordx4 v[4:5], off
	v_mad_u64_u32 v[4:5], s[0:1], s14, v232, v[174:175]
	s_or_b32 s0, s14, 1
	v_lshl_add_u64 v[4:5], v[4:5], 0, s[22:23]
	s_add_i32 m0, s16, 0x2000
	s_min_i32 s8, s0, s26
	global_load_lds_dwordx4 v[4:5], off
	v_mad_i64_i32 v[4:5], s[0:1], s8, v232, v[172:173]
	v_lshl_add_u64 v[4:5], v[4:5], 0, s[18:19]
	s_add_i32 m0, s16, 0x4000
	v_lshlrev_b32_e32 v0, 4, v3
	global_load_lds_dwordx4 v[4:5], off
	v_mad_i64_i32 v[4:5], s[0:1], s8, v232, v[174:175]
	s_add_i32 s0, s14, 2
	v_lshl_add_u64 v[4:5], v[4:5], 0, s[22:23]
	s_add_i32 m0, s16, 0x6000
	s_min_i32 s8, s0, s26
	global_load_lds_dwordx4 v[4:5], off
	v_mad_i64_i32 v[4:5], s[0:1], s8, v232, v[172:173]
	v_lshl_add_u64 v[4:5], v[4:5], 0, s[18:19]
	s_add_i32 m0, s16, 0x8000
	v_and_b32_e32 v0, 0xc0, v0
	global_load_lds_dwordx4 v[4:5], off
	v_mad_i64_i32 v[4:5], s[0:1], s8, v232, v[174:175]
	s_add_i32 s0, s14, 3
	v_lshl_add_u64 v[4:5], v[4:5], 0, s[22:23]
	s_add_i32 m0, s16, 0xa000
	s_min_i32 s8, s0, s26
	global_load_lds_dwordx4 v[4:5], off
	v_mad_i64_i32 v[4:5], s[0:1], s8, v232, v[172:173]
	v_lshl_add_u64 v[4:5], v[4:5], 0, s[18:19]
	s_add_i32 m0, s16, 0xc000
	v_lshl_or_b32 v0, v184, 8, v0
	global_load_lds_dwordx4 v[4:5], off
	v_mad_i64_i32 v[4:5], s[0:1], s8, v232, v[174:175]
	v_lshl_add_u64 v[4:5], v[4:5], 0, s[22:23]
	s_add_i32 m0, s16, 0xe000
	v_cmp_lt_i32_e64 s[38:39], 3, v8
	global_load_lds_dwordx4 v[4:5], off
	s_waitcnt vmcnt(6) lgkmcnt(0)
	s_barrier
; template <int MODE, int NQ, int TS, bool FAST = false> ...
;     ...
;       m2[nq] = (MODE == 2) ? sink2 : -1e30f; l[nq] = 0.f;
; #pragma unroll
;       for (int r = 0; r < 16; ++r) { o[nq][0][r] = 0.f; o[nq][1][r] = 0.f; }
;     ...
;   int kfo4[4];
; #pragma unroll
;   for (int ks = 0; ks < 4; ++ks) kfo4[ks] = r32 * 128 + (((2 * ks + hh) ^ ((r32 >> 1) & 7)) << 4);
;   const int vfo = 8192 + (4 * hh + ((lane & 15) >> 2)) * 64 + ((lane >> 4) & 1) * 32 + (lane & 3) * 8;
;   const bool g2 = wave >= 4;
	v_mul_f32_e32 v183, 0x3fb8aa3b, v250
	v_lshlrev_b32_e32 v4, 1, v3
	v_and_b32_e32 v4, 32, v4
	v_lshlrev_b32_e32 v5, 3, v13
	v_or3_b32 v188, v0, v4, v5
	v_cmp_gt_i32_e64 s[40:41], 4, v8
	s_cmp_ge_i32 s14, s15
	s_cbranch_scc1 .LBB0_242
	v_lshrrev_b32_e32 v0, 1, v3
	v_lshlrev_b32_e32 v6, 7, v2
	v_bitop3_b32 v0, v184, v0, 7 bitop3:0x78
	v_lshl_or_b32 v191, v0, 4, v6
	v_lshlrev_b32_e32 v0, 2, v184
	v_add3_u32 v0, v182, s7, v0
	s_and_b32 s0, s4, 0x7f80
	v_bfe_u32 v4, v3, 1, 3
	v_lshlrev_b32_e32 v3, 5, v3
	v_sub_u32_e32 v0, v0, v2
	v_bitop3_b32 v5, v184, v4, 6 bitop3:0x36
	v_and_b32_e32 v3, 0x1800, v3
	v_subrev_u32_e32 v0, s0, v0
	v_lshl_or_b32 v167, v5, 4, v6
	v_bitop3_b32 v5, v184, v4, 4 bitop3:0x36
	v_bitop3_b32 v4, v184, v4, 2 bitop3:0x36
	v_lshl_add_u32 v3, s14, 8, v3
	v_lshlrev_b32_e32 v0, 2, v0
	s_mov_b32 s0, 0x18380
	v_mov_b32_e32 v14, v1
	v_mov_b32_e32 v15, v1
	v_lshl_or_b32 v171, v5, 4, v6
	v_lshl_or_b32 v190, v4, 4, v6
	v_add3_u32 v192, v3, v0, s0
	v_mov_b32_e32 v0, v1
	v_mov_b32_e32 v2, v1
	v_mov_b32_e32 v3, v1
	v_mov_b32_e32 v4, v1
	v_mov_b32_e32 v5, v1
	v_mov_b32_e32 v6, v1
	v_mov_b32_e32 v7, v1
	v_mov_b32_e32 v8, v1
	v_mov_b32_e32 v9, v1
	v_mov_b32_e32 v10, v1
	v_mov_b32_e32 v11, v1
	v_mov_b32_e32 v12, v1
	v_mov_b32_e32 v13, v1
	v_mov_b64_e32 v[64:65], v[14:15]
	v_mov_b64_e32 v[48:49], v[14:15]
	v_mov_b64_e32 v[32:33], v[14:15]
	v_mov_b64_e32 v[62:63], v[12:13]
	v_mov_b64_e32 v[60:61], v[10:11]
	v_mov_b64_e32 v[58:59], v[8:9]
	v_mov_b64_e32 v[56:57], v[6:7]
	v_mov_b64_e32 v[54:55], v[4:5]
	v_mov_b64_e32 v[52:53], v[2:3]
	v_mov_b64_e32 v[50:51], v[0:1]
	v_mov_b64_e32 v[46:47], v[12:13]
	v_mov_b64_e32 v[44:45], v[10:11]
	v_mov_b64_e32 v[42:43], v[8:9]
	v_mov_b64_e32 v[40:41], v[6:7]
	v_mov_b64_e32 v[38:39], v[4:5]
	v_mov_b64_e32 v[36:37], v[2:3]
	v_mov_b64_e32 v[34:35], v[0:1]
	v_mov_b64_e32 v[30:31], v[12:13]
	v_mov_b64_e32 v[28:29], v[10:11]
	v_mov_b64_e32 v[26:27], v[8:9]
	v_mov_b64_e32 v[24:25], v[6:7]
	v_mov_b64_e32 v[22:23], v[4:5]
	v_mov_b64_e32 v[20:21], v[2:3]
	v_mov_b64_e32 v[18:19], v[0:1]
	v_mov_b64_e32 v[16:17], v[14:15]
	s_mov_b32 s0, 0
	v_mov_b32_e32 v185, 0
	v_mov_b32_e32 v187, v183
	v_mov_b32_e32 v189, v183
	v_mov_b32_e32 v186, 0
	v_mov_b64_e32 v[14:15], v[12:13]
	v_mov_b64_e32 v[12:13], v[10:11]
	v_mov_b64_e32 v[10:11], v[8:9]
	v_mov_b64_e32 v[8:9], v[6:7]
	v_mov_b64_e32 v[6:7], v[4:5]
	v_mov_b64_e32 v[4:5], v[2:3]
	v_mov_b64_e32 v[2:3], v[0:1]
	s_mov_b32 s27, s14
	s_mov_b32 s12, 0xf149f2ca
	s_waitcnt vmcnt(0)

; template <int MODE, int NQ, int TS, bool FAST = false> ...
;     ...
;     if (MODE == 0) {
;       const size_t tok = (size_t)(seq_base + q0w + 32 * nq + r32);
;       const bf16_t* po = part_o + tok * 512 + ooff + 4 * hh; const float* pm = part_ml + (tok * 8 + (ooff >> 6)) * 2;
;       m2[nq] = pm[0]; l[nq] = hh ? 0.f : pm[1];
; #pragma unroll
;       for (int g = 0; g < 4; ++g) { const uint2 a = *(const uint2*)(po + 8 * g), b = *(const uint2*)(po + 32 + 8 * g);
;         o[nq][0][4 * g] = bflo(a.x); o[nq][0][4 * g + 1] = bfhi(a.x); o[nq][0][4 * g + 2] = bflo(a.y); o[nq][0][4 * g + 3] = bfhi(a.y);
;         o[nq][1][4 * g] = bflo(b.x); o[nq][1][4 * g + 1] = bfhi(b.x); o[nq][1][4 * g + 2] = bflo(b.y); o[nq][1][4 * g + 3] = bfhi(b.y); }
;     } else {
;       m2[nq] = (MODE == 2) ? sink2 : -1e30f; l[nq] = 0.f;
; #pragma unroll
;       for (int r = 0; r < 16; ++r) { o[nq][0][r] = 0.f; o[nq][1][r] = 0.f; }
;     }
;   }
;   PG8_LAS unsigned char* L = (PG8_LAS unsigned char*)lds;
;   const int kkey_ = wave * 8 + (lane >> 3);
;   const bf16_t* kg = proj + (size_t)(seq_base + TS * kkey_) * ld + koff + (((lane & 7) ^ ((kkey_ >> 1) & 7)) * 8);
;   const bf16_t* vg = proj + (size_t)(seq_base + TS * ((wave & 3) * 16 + (lane >> 2))) * ld + voff + ((wave >> 2) * 4 + (lane & 3)) * 8;
;   const unsigned sdst = (unsigned)__builtin_amdgcn_readfirstlane(wave * 1024);
;     ...
;   const int ktl = kt1 - 1;
;   constexpr int TAB_OFF = 6 * 16384, TAB_N = (MODE == 3) ? 640 : 1024, TAB_ZERO = TAB_N / 2;
;   if (MODE == 0 || MODE == 3) {
;     float* tab = (float*)(lds + TAB_OFF);
;     for (int e = tid; e < TAB_N; e += 512) {
;       const int oo = e - TAB_ZERO, aa = oo < 0 ? -oo : oo;
;       if (MODE == 0) {
;         const int c = (aa <= 64 ? 1 : 0) + (((oo & 3) == 0 && aa <= 256) ? 1 : 0) + (((oo & 15) == 0 && aa <= 256) ? 1 : 0);
;         tab[e] = c ? (-slope2 * (float)aa + (c == 1 ? 0.f : (c == 2 ? 1.f : 1.5849625007f))) : -1e30f;
;       } else {
;         tab[e] = (aa >= 17 && aa <= 64) ? -slope2 * (float)(16 * aa) : -1e30f;
;       }
;     }
;   }
;   if (MODE == 2) {
;     float* tab = (float*)(lds + TAB_OFF) + (wave & 3) * 512;
; #pragma unroll
;     for (int i = 0; i < 4; ++i) { const int e = (wave >> 2) * 64 + lane + 128 * i; const int oo = e - 256, aa = oo < 0 ? -oo : oo; tab[e] = (aa <= 128) ? -slope2 * (float)aa : -1e30f; }
;   }
.LBB0_377:
	s_or_b64 exec, exec, s[28:29]
	s_and_b64 s[0:1], s[26:27], exec
	s_cselect_b32 s0, 0x100, 64
	s_add_i32 s1, s7, 0x1ff
	v_lshrrev_b32_e32 v0, 3, v40
	s_ashr_i32 s1, s1, 6
	v_lshl_or_b32 v0, v38, 3, v0
	s_add_i32 s5, s1, 1
	v_add_u32_e32 v35, s6, v0
	v_lshrrev_b32_e32 v0, 1, v0
	s_cmp_lt_i32 s1, s0
	v_mov_b64_e32 v[42:43], s[66:67]
	v_xor_b32_e32 v0, v0, v34
	s_cselect_b32 s5, s5, s0
	v_mad_i64_i32 v[42:43], s[0:1], v35, s22, v[42:43]
	v_lshlrev_b32_e32 v0, 4, v0
	v_lshl_add_u64 v[42:43], v[42:43], 0, s[76:77]
	v_and_b32_e32 v0, 0x70, v0
	v_lshl_add_u64 v[84:85], v[42:43], 0, v[0:1]
	v_lshlrev_b32_e32 v0, 4, v38
	v_and_b32_e32 v0, 48, v0
	v_lshrrev_b32_e32 v35, 2, v40
	v_or3_b32 v0, v35, v0, s6
	v_mul_u32_u24_e32 v0, 0x900, v0
	v_lshlrev_b32_e32 v0, 1, v0
	s_mov_b32 s0, 0x1ffffffc
	v_lshl_add_u64 v[40:41], s[66:67], 0, v[0:1]
	v_and_or_b32 v0, v38, s0, v39
	s_addk_i32 s7, 0xff00
	v_lshlrev_b32_e32 v42, 3, v0
	s_ashr_i32 s16, s7, 6
	v_lshl_add_u64 v[40:41], v[40:41], 0, s[76:77]
	v_ashrrev_i32_e32 v43, 31, v42
	s_max_i32 s7, s16, 0
	v_lshl_add_u64 v[86:87], v[42:43], 1, v[40:41]
	s_lshl_b32 s15, s8, 10
	v_mad_u64_u32 v[40:41], s[0:1], s7, v237, v[84:85]
	s_mov_b64 s[26:27], 0x400
	v_lshl_add_u64 v[40:41], v[40:41], 0, s[26:27]
	s_mov_b32 m0, s15
	s_add_i32 s14, s5, -1
	global_load_lds_dwordx4 v[40:41], off
	v_mad_u64_u32 v[40:41], s[0:1], s7, v237, v[86:87]
	s_mov_b64 s[18:19], 0x800
	s_or_b32 s8, s7, 1
	v_lshl_add_u64 v[40:41], v[40:41], 0, s[18:19]
	s_add_i32 m0, s15, 0x2000
	s_min_i32 s12, s8, s14
	global_load_lds_dwordx4 v[40:41], off
	v_mad_i64_i32 v[40:41], s[0:1], s12, v237, v[84:85]
	v_lshl_add_u64 v[40:41], v[40:41], 0, s[26:27]
	s_add_i32 m0, s15, 0x4000
	v_lshlrev_b32_e32 v0, 4, v34
	global_load_lds_dwordx4 v[40:41], off
	v_mad_i64_i32 v[40:41], s[0:1], s12, v237, v[86:87]
	s_or_b32 s0, s7, 2
	v_lshl_add_u64 v[40:41], v[40:41], 0, s[18:19]
	s_add_i32 m0, s15, 0x6000
	s_min_i32 s12, s0, s14
	global_load_lds_dwordx4 v[40:41], off
	v_mad_i64_i32 v[40:41], s[0:1], s12, v237, v[84:85]
	v_lshl_add_u64 v[40:41], v[40:41], 0, s[26:27]
	s_add_i32 m0, s15, 0x8000
	v_and_b32_e32 v0, 0xc0, v0
	global_load_lds_dwordx4 v[40:41], off
	v_mad_i64_i32 v[40:41], s[0:1], s12, v237, v[86:87]
	s_or_b32 s0, s7, 3
	v_lshl_add_u64 v[40:41], v[40:41], 0, s[18:19]
	s_add_i32 m0, s15, 0xa000
	s_min_i32 s12, s0, s14
	global_load_lds_dwordx4 v[40:41], off
	v_mad_i64_i32 v[40:41], s[0:1], s12, v237, v[84:85]
	v_lshl_add_u64 v[40:41], v[40:41], 0, s[26:27]
	s_add_i32 m0, s15, 0xc000
	v_lshlrev_b32_e32 v35, 1, v34
	global_load_lds_dwordx4 v[40:41], off
	v_mad_i64_i32 v[40:41], s[0:1], s12, v237, v[86:87]
	v_lshl_add_u64 v[40:41], v[40:41], 0, s[18:19]
	s_add_i32 m0, s15, 0xe000
	v_lshl_or_b32 v0, v37, 8, v0
	global_load_lds_dwordx4 v[40:41], off
	s_waitcnt vmcnt(6) lgkmcnt(0)
	s_barrier
	v_and_b32_e32 v35, 32, v35
	v_lshlrev_b32_e32 v39, 3, v39
	v_lshlrev_b32_e32 v95, 2, v37
	v_lshlrev_b32_e32 v18, 16, v2
	v_and_b32_e32 v19, 0xffff0000, v2
	v_lshlrev_b32_e32 v20, 16, v3
	v_and_b32_e32 v21, 0xffff0000, v3
	v_lshlrev_b32_e32 v2, 16, v4
	v_and_b32_e32 v3, 0xffff0000, v4
	v_lshlrev_b32_e32 v4, 16, v5
	v_and_b32_e32 v5, 0xffff0000, v5
	v_lshlrev_b32_e32 v22, 16, v6
	v_and_b32_e32 v23, 0xffff0000, v6
	v_lshlrev_b32_e32 v24, 16, v7
	v_and_b32_e32 v25, 0xffff0000, v7
	v_lshlrev_b32_e32 v6, 16, v8
	v_and_b32_e32 v7, 0xffff0000, v8
	v_lshlrev_b32_e32 v8, 16, v9
	v_and_b32_e32 v9, 0xffff0000, v9
	v_lshlrev_b32_e32 v26, 16, v10
	v_and_b32_e32 v27, 0xffff0000, v10
	v_lshlrev_b32_e32 v28, 16, v11
	v_and_b32_e32 v29, 0xffff0000, v11
	v_lshlrev_b32_e32 v10, 16, v12
	v_and_b32_e32 v11, 0xffff0000, v12
	v_lshlrev_b32_e32 v12, 16, v13
	v_and_b32_e32 v13, 0xffff0000, v13
	v_lshlrev_b32_e32 v30, 16, v14
	v_and_b32_e32 v31, 0xffff0000, v14
	v_lshlrev_b32_e32 v32, 16, v15
	v_and_b32_e32 v33, 0xffff0000, v15
	v_lshlrev_b32_e32 v14, 16, v16
	v_and_b32_e32 v15, 0xffff0000, v16
	v_lshlrev_b32_e32 v16, 16, v17
	v_and_b32_e32 v17, 0xffff0000, v17
	s_mov_b32 s9, 0
	v_or3_b32 v96, v0, v35, v39
	v_cmp_lt_i32_e64 s[38:39], 3, v38
	v_cmp_gt_i32_e64 s[40:41], 4, v38
	s_cmp_lt_i32 s7, s5
	s_cbranch_scc0 .LBB0_410
	s_add_i32 s0, s7, 4
	s_min_u32 s9, s0, s14
	v_mad_u64_u32 v[38:39], s[0:1], s9, v237, v[84:85]
	v_lshl_add_u64 v[38:39], v[38:39], 0, s[26:27]
	s_add_i32 m0, s15, 0x10000
	v_lshrrev_b32_e32 v0, 1, v34
	global_load_lds_dwordx4 v[38:39], off
	v_mad_u64_u32 v[38:39], s[0:1], s9, v237, v[86:87]
	v_lshl_add_u64 v[38:39], v[38:39], 0, s[18:19]
	s_add_i32 m0, s15, 0x12000
	v_bfe_u32 v34, v34, 1, 3
	global_load_lds_dwordx4 v[38:39], off
	s_lshl_b32 s30, s7, 6
	v_bitop3_b32 v35, v37, v34, 6 bitop3:0x36
	v_lshlrev_b32_e32 v38, 7, v103
	v_add_u32_e32 v101, 0xffffff00, v93
	v_add_u32_e32 v102, 0x11f, v93
	s_or_b32 s0, s30, 63
	v_lshl_or_b32 v97, v35, 4, v38
	v_bitop3_b32 v35, v37, v34, 4 bitop3:0x36
	v_bitop3_b32 v34, v37, v34, 2 bitop3:0x36
	v_bitop3_b32 v0, v37, v0, 7 bitop3:0x78
	v_cmp_ge_i32_e32 vcc, s0, v101
	v_cmp_le_i32_e64 s[0:1], s30, v102
	s_mov_b64 s[60:61], 0x400
	s_mov_b64 s[58:59], 0x800
	v_lshl_or_b32 v98, v35, 4, v38
	v_lshl_or_b32 v99, v34, 4, v38
	v_lshl_or_b32 v100, v0, 4, v38
	v_sub_u32_e32 v0, v95, v36
	s_and_b64 s[0:1], vcc, s[0:1]
	s_and_saveexec_b64 s[12:13], s[40:41]
	s_xor_b64 s[26:27], exec, s[12:13]
	s_cbranch_execz .LBB0_384
	s_and_saveexec_b64 s[78:79], s[0:1]
	s_cbranch_execz .LBB0_383
; #define MFMA32(a, b, c) __builtin_amdgcn_mfma_f32_32x32x16_bf16((a), (b), (c), 0, 0, 0)
; template <int MODE, int NQ, int TS, bool FAST = false> ...
;     ...
;   auto QK = [&](int slot) {
;     const char* kb_ = lds + slot * 16384;
; #pragma unroll
;     for (int nq = 0; nq < NQ; ++nq)
; #pragma unroll
;       for (int r = 0; r < 16; ++r) { s[nq][0][r] = 0.f; s[nq][1][r] = 0.f; }
; #pragma unroll
;     for (int ks = 0; ks < 4; ++ks) {
;       const bf16x8 k0 = *(const bf16x8*)(kb_ + kfo4[ks]), k1 = *(const bf16x8*)(kb_ + kfo4[ks] + 4096);
; #pragma unroll
;       for (int nq = 0; nq < NQ; ++nq) { s[nq][0] = MFMA32(k0, qf[nq][ks], s[nq][0]); s[nq][1] = MFMA32(k1, qf[nq][ks], s[nq][1]); }
;     }
;   };
;   auto SM = [&](int kt) {
; #pragma unroll
;     for (int nq = 0; nq < NQ; ++nq) {
;       f32x16& s0 = s[nq][0]; f32x16& s1 = s[nq][1];
;       float mx = -1e30f;
;       if (MODE == 1) {
;       } else if (MODE == 0 || MODE == 3) {
;         const float* tb = (const float*)(lds + TAB_OFF) + (kt * 64 + 4 * hh - (q0w + 32 * nq + r32) + TAB_ZERO);
; #pragma unroll
;         for (int r = 0; r < 16; ++r) {
;           const float va = fmaf(s0[r], C2, tb[(r & 3) + 8 * (r >> 2)]), vb = fmaf(s1[r], C2, tb[(r & 3) + 8 * (r >> 2) + 32]);
;           s0[r] = va; s1[r] = vb; mx = fmaxf(mx, fmaxf(va, vb));
;         }
;       } else {
;         const float* tb = (const float*)(lds + TAB_OFF) + (wave & 3) * 512 + (kt * 64 + 4 * hh - (q0w + 32 * nq + r32) + 256);
; #pragma unroll
;         for (int r = 0; r < 16; ++r) {
;           const float va = fmaf(s0[r], C2, tb[(r & 3) + 8 * (r >> 2)]), vb = fmaf(s1[r], C2, tb[(r & 3) + 8 * (r >> 2) + 32]);
;           s0[r] = va; s1[r] = vb; mx = fmaxf(mx, fmaxf(va, vb));
;         }
;       }
;       float mn;
;       if (MODE == 1) {
;         mn = sink2;
;       } else {
;         if (__any(mx > m2[nq] + 8.f)) {
;           mx = fmaxf(mx, __shfl_xor(mx, 32));
;           mn = fmaxf(m2[nq], mx);
;           const float alpha = __builtin_amdgcn_exp2f(m2[nq] - mn);
;           l[nq] *= alpha;
; #pragma unroll
;           for (int r = 0; r < 16; ++r) { o[nq][0][r] *= alpha; o[nq][1][r] *= alpha; }
;           m2[nq] = mn;
;         }
;         mn = m2[nq];
	ds_read_b128 v[34:37], v100
	ds_read_b128 v[50:53], v100 offset:4096
	ds_read_b128 v[88:91], v99
	ds_read_b128 v[104:107], v99 offset:4096
	v_lshlrev_b32_e32 v0, 2, v0
	s_waitcnt lgkmcnt(0)
	v_mfma_f32_32x32x16_bf16 v[34:49], v[34:37], v[66:69], 0
	v_mfma_f32_32x32x16_bf16 v[50:65], v[50:53], v[66:69], 0
	v_mfma_f32_32x32x16_bf16 v[34:49], v[88:91], v[70:73], v[34:49]
	v_mfma_f32_32x32x16_bf16 v[50:65], v[104:107], v[70:73], v[50:65]
	ds_read_b128 v[88:91], v98
	ds_read_b128 v[104:107], v98 offset:4096
	s_waitcnt lgkmcnt(0)
	v_mfma_f32_32x32x16_bf16 v[34:49], v[88:91], v[74:77], v[34:49]
	v_mfma_f32_32x32x16_bf16 v[50:65], v[104:107], v[74:77], v[50:65]
	ds_read_b128 v[88:91], v97
	ds_read_b128 v[104:107], v97 offset:4096
	s_waitcnt lgkmcnt(0)
	v_mfma_f32_32x32x16_bf16 v[34:49], v[88:91], v[78:81], v[34:49]
	v_mfma_f32_32x32x16_bf16 v[50:65], v[104:107], v[78:81], v[50:65]
	v_lshl_add_u32 v104, s30, 2, v0
	v_add_u32_e32 v0, 0x18800, v104
	ds_read2_b32 v[88:89], v0 offset1:1
	s_waitcnt lgkmcnt(0)
	s_nop 6
	v_fmamk_f32 v0, v34, 0x3e38aa3b, v88
	v_add_u32_e32 v34, 0x18880, v104
	ds_read2_b32 v[90:91], v34 offset1:1
	v_fmac_f32_e32 v89, 0x3e38aa3b, v35
	s_waitcnt lgkmcnt(0)
	v_fmamk_f32 v88, v50, 0x3e38aa3b, v90
	v_fmac_f32_e32 v91, 0x3e38aa3b, v51
	v_max_f32_e32 v34, v0, v88
	v_max_f32_e32 v35, v89, v91
	v_max3_f32 v90, v34, s23, v35
	v_add_u32_e32 v34, 0x18808, v104
	ds_read2_b32 v[34:35], v34 offset1:1
	s_waitcnt lgkmcnt(0)
	v_fmamk_f32 v34, v36, 0x3e38aa3b, v34
	v_add_u32_e32 v36, 0x18888, v104
	ds_read2_b32 v[50:51], v36 offset1:1
	v_fmac_f32_e32 v35, 0x3e38aa3b, v37
	s_waitcnt lgkmcnt(0)
	v_fmamk_f32 v50, v52, 0x3e38aa3b, v50
	v_fmac_f32_e32 v51, 0x3e38aa3b, v53
	v_max_f32_e32 v36, v34, v50
	v_max_f32_e32 v37, v35, v51
	v_max3_f32 v90, v90, v36, v37
	v_add_u32_e32 v36, 0x18820, v104
	ds_read2_b32 v[36:37], v36 offset1:1
	s_waitcnt lgkmcnt(0)
	v_fmamk_f32 v36, v38, 0x3e38aa3b, v36
	v_add_u32_e32 v38, 0x188a0, v104
	ds_read2_b32 v[52:53], v38 offset1:1
	v_fmac_f32_e32 v37, 0x3e38aa3b, v39
	s_waitcnt lgkmcnt(0)
	v_fmamk_f32 v52, v54, 0x3e38aa3b, v52
	v_fmac_f32_e32 v53, 0x3e38aa3b, v55
	v_max_f32_e32 v38, v36, v52
	v_max_f32_e32 v39, v37, v53
	v_max3_f32 v90, v90, v38, v39
	v_add_u32_e32 v38, 0x18828, v104
	ds_read2_b32 v[38:39], v38 offset1:1
	s_waitcnt lgkmcnt(0)
	v_fmamk_f32 v38, v40, 0x3e38aa3b, v38
	v_add_u32_e32 v40, 0x188a8, v104
	ds_read2_b32 v[54:55], v40 offset1:1
	v_fmac_f32_e32 v39, 0x3e38aa3b, v41
	s_waitcnt lgkmcnt(0)
	v_fmamk_f32 v54, v56, 0x3e38aa3b, v54
	v_fmac_f32_e32 v55, 0x3e38aa3b, v57
	v_max_f32_e32 v40, v38, v54
	v_max_f32_e32 v41, v39, v55
	v_max3_f32 v90, v90, v40, v41
	v_add_u32_e32 v40, 0x18840, v104
	ds_read2_b32 v[40:41], v40 offset1:1
	s_waitcnt lgkmcnt(0)
	v_fmamk_f32 v40, v42, 0x3e38aa3b, v40
	v_add_u32_e32 v42, 0x188c0, v104
	ds_read2_b32 v[56:57], v42 offset1:1
	v_fmac_f32_e32 v41, 0x3e38aa3b, v43
	s_waitcnt lgkmcnt(0)
	v_fmamk_f32 v56, v58, 0x3e38aa3b, v56
	v_fmac_f32_e32 v57, 0x3e38aa3b, v59
	v_max_f32_e32 v42, v40, v56
	v_max_f32_e32 v43, v41, v57
	v_max3_f32 v90, v90, v42, v43
	v_add_u32_e32 v42, 0x18848, v104
	ds_read2_b32 v[42:43], v42 offset1:1
	s_waitcnt lgkmcnt(0)
	v_fmamk_f32 v42, v44, 0x3e38aa3b, v42
	v_add_u32_e32 v44, 0x188c8, v104
	ds_read2_b32 v[58:59], v44 offset1:1
	v_fmac_f32_e32 v43, 0x3e38aa3b, v45
	s_waitcnt lgkmcnt(0)
	v_fmamk_f32 v58, v60, 0x3e38aa3b, v58
	v_fmac_f32_e32 v59, 0x3e38aa3b, v61
	v_max_f32_e32 v44, v42, v58
	v_max_f32_e32 v45, v43, v59
	v_max3_f32 v90, v90, v44, v45
	v_add_u32_e32 v44, 0x18860, v104
	ds_read2_b32 v[44:45], v44 offset1:1
	s_waitcnt lgkmcnt(0)
	v_fmamk_f32 v44, v46, 0x3e38aa3b, v44
	v_add_u32_e32 v46, 0x188e0, v104
	ds_read2_b32 v[60:61], v46 offset1:1
	v_fmac_f32_e32 v45, 0x3e38aa3b, v47
	s_waitcnt lgkmcnt(0)
	v_fmamk_f32 v60, v62, 0x3e38aa3b, v60
	v_fmac_f32_e32 v61, 0x3e38aa3b, v63
	v_max_f32_e32 v46, v44, v60
	v_max_f32_e32 v47, v45, v61
	v_max3_f32 v90, v90, v46, v47
	v_add_u32_e32 v46, 0x18868, v104
	ds_read2_b32 v[46:47], v46 offset1:1
	s_waitcnt lgkmcnt(0)
	v_fmamk_f32 v46, v48, 0x3e38aa3b, v46
	v_add_u32_e32 v48, 0x188e8, v104
	ds_read2_b32 v[62:63], v48 offset1:1
	v_fmac_f32_e32 v47, 0x3e38aa3b, v49
	s_waitcnt lgkmcnt(0)
	v_fmamk_f32 v48, v64, 0x3e38aa3b, v62
	v_fmac_f32_e32 v63, 0x3e38aa3b, v65
	v_max_f32_e32 v62, v46, v48
	v_max_f32_e32 v49, v47, v63
	v_max3_f32 v49, v90, v62, v49
	v_add_f32_e32 v62, 0x41000000, v94
	v_cmp_gt_f32_e32 vcc, v49, v62
	s_cbranch_vccz .LBB0_382
	ds_bpermute_b32 v62, v163, v49
	s_waitcnt lgkmcnt(0)
	v_max3_f32 v49, v94, v49, v62
	v_sub_f32_e32 v62, v94, v49
	v_exp_f32_e32 v62, v62
	v_mov_b32_e32 v94, v49
	v_mul_f32_e32 v92, v92, v62
	v_pk_mul_f32 v[32:33], v[62:63], v[32:33] op_sel_hi:[0,1]
	v_pk_mul_f32 v[30:31], v[62:63], v[30:31] op_sel_hi:[0,1]
	v_pk_mul_f32 v[28:29], v[62:63], v[28:29] op_sel_hi:[0,1]
	v_pk_mul_f32 v[26:27], v[62:63], v[26:27] op_sel_hi:[0,1]
	v_pk_mul_f32 v[24:25], v[62:63], v[24:25] op_sel_hi:[0,1]
	v_pk_mul_f32 v[22:23], v[62:63], v[22:23] op_sel_hi:[0,1]
	v_pk_mul_f32 v[20:21], v[62:63], v[20:21] op_sel_hi:[0,1]
	v_pk_mul_f32 v[18:19], v[62:63], v[18:19] op_sel_hi:[0,1]
	v_pk_mul_f32 v[16:17], v[62:63], v[16:17] op_sel_hi:[0,1]
	v_pk_mul_f32 v[14:15], v[62:63], v[14:15] op_sel_hi:[0,1]
	v_pk_mul_f32 v[12:13], v[62:63], v[12:13] op_sel_hi:[0,1]
	v_pk_mul_f32 v[10:11], v[62:63], v[10:11] op_sel_hi:[0,1]
	v_pk_mul_f32 v[8:9], v[62:63], v[8:9] op_sel_hi:[0,1]
	v_pk_mul_f32 v[6:7], v[62:63], v[6:7] op_sel_hi:[0,1]
	v_pk_mul_f32 v[4:5], v[62:63], v[4:5] op_sel_hi:[0,1]
	v_pk_mul_f32 v[2:3], v[62:63], v[2:3] op_sel_hi:[0,1]
